# P1 epilogue: whole-line (8 rows x 128 B) write-through stores via permuted weight rows
# speedup vs baseline: 1.0446x; 1.0073x over previous
; __device__ __forceinline__ void tr_tile(const float* W, int K, int N, int kt, int nt, LAS float* tile, const float* kscale, h16* dst, int mode, h16* dstG) {
;     ...
;     {
;         const int n = tid >> 3, kc = (tid & 7) * 8, gn = n0 + n;
;         if (gn < N) {
;             h16x8 o;
; #pragma unroll
;             for (int j = 0; j < 8; ++j) o[j] = (h16)tile[(kc + j) * 65 + n];
;             h16* d;
;             if (mode == 0) d = dst + (size_t)gn * K;
;             else d = (gn < 2048) ? dst + (size_t)gn * K : (gn < 2064 ? dstG + (size_t)(gn - 2048) * K : dst + (size_t)(gn - 16) * K);
;             *(h16x8*)(d + k0 + kc) = o;
;         }
.LBB0_22:
	s_or_b64 exec, exec, s[30:31]
	v_and_b32_e32 v44, 0xe0, v2
	v_lshrrev_b32_e32 v45, 1, v44
	v_lshlrev_b32_e32 v44, 2, v44
	v_and_b32_e32 v44, 0x80, v44
	v_and_b32_e32 v45, 0x60, v45
	v_or_b32_e32 v45, v45, v44
	v_and_b32_e32 v2, 0xffffff1f, v2
	v_or_b32_e32 v2, v2, v45
	v_lshlrev_b64 v[2:3], 11, v[2:3]
	v_lshl_add_u64 v[2:3], v[30:31], 0, v[2:3]
	s_ashr_i32 s11, s10, 31
	v_lshl_add_u64 v[2:3], s[10:11], 1, v[2:3]
	s_waitcnt lgkmcnt(0)
	v_cvt_pk_f16_f32 v43, v28, v29
	v_cvt_pk_f16_f32 v42, v8, v9
	v_cvt_pk_f16_f32 v41, v6, v7
	v_cvt_pk_f16_f32 v40, v4, v5
	v_lshl_add_u64 v[2:3], v[2:3], 0, v[10:11]
	global_store_dwordx4 v[2:3], v[40:43], off sc0 sc1

; #define PG8_STAGE(bufoff, gbase, voff) do { _Pragma("unroll") for (int _i = 0; _i < 2; ++_i) \
;         __builtin_amdgcn_global_load_lds((const unsigned*)((const char*)(gbase) + (voff)[_i]), (LAS unsigned*)(lds + (bufoff) + ldsw + _i * 8192), 16, 0, 0); } while (0)
; #define PG8_LDA(dst, b, h) do { _Pragma("unroll") for (int m = 0; m < 4; ++m) _Pragma("unroll") for (int k = 0; k < 2; ++k) dst[m][k] = *(const LAS h16x8*)(lds + PG8_SA(b, h) + aoff + m * 2048 + k * 1024); } while (0)
; #define PG8_LDB(dst, b, h) do { _Pragma("unroll") for (int n = 0; n < 2; ++n) _Pragma("unroll") for (int k = 0; k < 2; ++k) dst[n][k] = *(const LAS h16x8*)(lds + PG8_SB(b, h) + boff + n * 2048 + k * 1024); } while (0)
; #define PG8_MMA(ai, bj, At, Bt) do { __builtin_amdgcn_s_setprio(1); _Pragma("unroll") for (int m = 0; m < 4; ++m) _Pragma("unroll") for (int n = 0; n < 2; ++n) _Pragma("unroll") for (int k = 0; k < 2; ++k) \
;         acc[ai][bj][m][n] = __builtin_amdgcn_mfma_f32_16x16x32_f16(Bt[n][k], At[m][k], acc[ai][bj][m][n], 0, 0, 0); __builtin_amdgcn_s_setprio(0); } while (0)
; #define PG8_WAIT_L(n) asm volatile("s_waitcnt lgkmcnt(" #n ")" ::: "memory")
; #define PG8_BAR __builtin_amdgcn_s_barrier()
; #define PG8_SCHED __builtin_amdgcn_sched_barrier(0)
; template <class Epi>
; __device__ __forceinline__ void gemm_phase(LAS unsigned char* lds, const Gemm g, const StaticOrder& S, const Epi& E) {
;     ...
;             PG8_LDB(B0, 0, 0); PG8_SCHED; PG8_LDA(At, 0, 0); PG8_STAGE(PG8_SA(1, 1), a1 + hstep, voffA);
;             PG8_WAIT_L(8); PG8_BAR; PG8_WAIT_L(0); PG8_MMA(0, 0, At, B0); PG8_BAR; PG8_SCHED;
;             PG8_LDB(B1, 0, 1); PG8_STAGE(PG8_SB(0, 0), b2, voffB);
;             PG8_BAR; PG8_WAIT_L(0); PG8_MMA(0, 1, At, B1); PG8_BAR;
;             PG8_LDA(At, 0, 1); PG8_STAGE(PG8_SA(0, 0), a2, voffA);
;             PG8_BAR; PG8_WAIT_L(0); PG8_MMA(1, 0, At, B0); PG8_BAR; PG8_SCHED;
.LBB0_84:
	ds_read_b128 v[162:165], v158
	ds_read_b128 v[166:169], v158 offset:1024
	ds_read_b128 v[170:173], v158 offset:2048
	ds_read_b128 v[174:177], v158 offset:3072
	s_add_u32 s38, s34, 0xfffc0080
	s_addc_u32 s39, s35, -1
	s_cmp_eq_u32 s96, 12
	s_cselect_b32 s43, s27, s39
	s_cselect_b32 s42, s88, s38
	s_cselect_b32 s39, s25, s95
	s_cselect_b32 s38, s92, s94
	v_lshl_add_u64 v[210:211], s[34:35], 0, v[150:151]
	s_add_i32 m0, s11, 0xc000
	ds_read_b128 v[178:181], v159
	ds_read_b128 v[182:185], v159 offset:1024
	ds_read_b128 v[186:189], v159 offset:2048
	ds_read_b128 v[190:193], v159 offset:3072
	ds_read_b128 v[194:197], v159 offset:4096
	ds_read_b128 v[198:201], v159 offset:5120
	ds_read_b128 v[202:205], v159 offset:6144
	ds_read_b128 v[206:209], v159 offset:7168
	global_load_lds_dwordx4 v[210:211], off
	v_lshl_add_u64 v[210:211], s[34:35], 0, v[152:153]
	s_add_i32 m0, s11, 0xe000
	s_nop 0
	global_load_lds_dwordx4 v[210:211], off
	s_waitcnt lgkmcnt(8)
	s_barrier
	s_waitcnt lgkmcnt(0)
	s_setprio 1
	s_waitcnt lgkmcnt(0)
	v_mfma_f32_16x16x32_f16 v[124:127], v[162:165], v[178:181], v[124:127]
	v_mfma_f32_16x16x32_f16 v[120:123], v[170:173], v[178:181], v[120:123]
	v_mfma_f32_16x16x32_f16 v[116:119], v[162:165], v[186:189], v[116:119]
	v_mfma_f32_16x16x32_f16 v[112:115], v[170:173], v[186:189], v[112:115]
	v_mfma_f32_16x16x32_f16 v[100:103], v[162:165], v[194:197], v[100:103]
	v_mfma_f32_16x16x32_f16 v[96:99], v[170:173], v[194:197], v[96:99]
	v_mfma_f32_16x16x32_f16 v[84:87], v[162:165], v[202:205], v[84:87]
	v_mfma_f32_16x16x32_f16 v[80:83], v[170:173], v[202:205], v[80:83]
	v_mfma_f32_16x16x32_f16 v[124:127], v[166:169], v[182:185], v[124:127]
	v_mfma_f32_16x16x32_f16 v[120:123], v[174:177], v[182:185], v[120:123]
	v_mfma_f32_16x16x32_f16 v[116:119], v[166:169], v[190:193], v[116:119]
	v_mfma_f32_16x16x32_f16 v[112:115], v[174:177], v[190:193], v[112:115]
	v_mfma_f32_16x16x32_f16 v[100:103], v[166:169], v[198:201], v[100:103]
	v_mfma_f32_16x16x32_f16 v[96:99], v[174:177], v[198:201], v[96:99]
	v_mfma_f32_16x16x32_f16 v[84:87], v[166:169], v[206:209], v[84:87]
	v_mfma_f32_16x16x32_f16 v[80:83], v[174:177], v[206:209], v[80:83]
	s_setprio 0
	s_barrier
	s_add_i32 s80, s60, s45
	v_lshl_add_u64 v[222:223], s[38:39], 0, v[128:129]
	s_mov_b32 m0, s80
	ds_read_b128 v[210:213], v160
	ds_read_b128 v[214:217], v160 offset:1024
	ds_read_b128 v[218:221], v160 offset:2048
	ds_read_b128 v[228:231], v160 offset:3072
	global_load_lds_dwordx4 v[222:223], off
	v_lshl_add_u64 v[232:233], s[38:39], 0, v[138:139]
	s_add_i32 m0, s80, 0x2000
	s_nop 0
	global_load_lds_dwordx4 v[232:233], off
	s_barrier
	s_waitcnt lgkmcnt(0)
	s_setprio 1
	s_waitcnt lgkmcnt(0)
	v_mfma_f32_16x16x32_f16 v[108:111], v[210:213], v[178:181], v[108:111]
	v_mfma_f32_16x16x32_f16 v[104:107], v[218:221], v[178:181], v[104:107]
	v_mfma_f32_16x16x32_f16 v[92:95], v[210:213], v[186:189], v[92:95]
	v_mfma_f32_16x16x32_f16 v[88:91], v[218:221], v[186:189], v[88:91]
	v_mfma_f32_16x16x32_f16 v[76:79], v[210:213], v[194:197], v[76:79]
	v_mfma_f32_16x16x32_f16 v[72:75], v[218:221], v[194:197], v[72:75]
	v_mfma_f32_16x16x32_f16 v[68:71], v[210:213], v[202:205], v[68:71]
	v_mfma_f32_16x16x32_f16 v[64:67], v[218:221], v[202:205], v[64:67]
	v_mfma_f32_16x16x32_f16 v[108:111], v[214:217], v[182:185], v[108:111]
	v_mfma_f32_16x16x32_f16 v[104:107], v[228:231], v[182:185], v[104:107]
	v_mfma_f32_16x16x32_f16 v[92:95], v[214:217], v[190:193], v[92:95]
	v_mfma_f32_16x16x32_f16 v[88:91], v[228:231], v[190:193], v[88:91]
	v_mfma_f32_16x16x32_f16 v[76:79], v[214:217], v[198:201], v[76:79]
	v_mfma_f32_16x16x32_f16 v[72:75], v[228:231], v[198:201], v[72:75]
	v_mfma_f32_16x16x32_f16 v[68:71], v[214:217], v[206:209], v[68:71]
	v_mfma_f32_16x16x32_f16 v[64:67], v[228:231], v[206:209], v[64:67]
	s_setprio 0
	s_mov_b32 m0, s11
	v_lshl_add_u64 v[234:235], s[42:43], 0, v[144:145]
	s_barrier
	ds_read_b128 v[178:181], v159 offset:16384
	ds_read_b128 v[182:185], v159 offset:17408
	ds_read_b128 v[186:189], v159 offset:18432
	ds_read_b128 v[190:193], v159 offset:19456
	ds_read_b128 v[194:197], v159 offset:20480
	ds_read_b128 v[198:201], v159 offset:21504
	ds_read_b128 v[202:205], v159 offset:22528
	ds_read_b128 v[206:209], v159 offset:23552
	global_load_lds_dwordx4 v[234:235], off
	v_lshl_add_u64 v[236:237], s[42:43], 0, v[140:141]
	s_mov_b32 m0, s53
	s_nop 0
	global_load_lds_dwordx4 v[236:237], off
	s_barrier
	s_waitcnt lgkmcnt(0)
	s_setprio 1
	s_waitcnt lgkmcnt(0)
	v_mfma_f32_16x16x32_f16 v[60:63], v[162:165], v[178:181], v[60:63]
	v_mfma_f32_16x16x32_f16 v[56:59], v[170:173], v[178:181], v[56:59]
	v_mfma_f32_16x16x32_f16 v[52:55], v[162:165], v[186:189], v[52:55]
	v_mfma_f32_16x16x32_f16 v[48:51], v[170:173], v[186:189], v[48:51]
	v_mfma_f32_16x16x32_f16 v[36:39], v[162:165], v[194:197], v[36:39]
	v_mfma_f32_16x16x32_f16 v[32:35], v[170:173], v[194:197], v[32:35]
	v_mfma_f32_16x16x32_f16 v[20:23], v[162:165], v[202:205], v[20:23]
	v_mfma_f32_16x16x32_f16 v[16:19], v[170:173], v[202:205], v[16:19]
	v_mfma_f32_16x16x32_f16 v[60:63], v[166:169], v[182:185], v[60:63]
	v_mfma_f32_16x16x32_f16 v[56:59], v[174:177], v[182:185], v[56:59]
	v_mfma_f32_16x16x32_f16 v[52:55], v[166:169], v[190:193], v[52:55]
	v_mfma_f32_16x16x32_f16 v[48:51], v[174:177], v[190:193], v[48:51]
	v_mfma_f32_16x16x32_f16 v[36:39], v[166:169], v[198:201], v[36:39]
	v_mfma_f32_16x16x32_f16 v[32:35], v[174:177], v[198:201], v[32:35]
	v_mfma_f32_16x16x32_f16 v[20:23], v[166:169], v[206:209], v[20:23]
	v_mfma_f32_16x16x32_f16 v[16:19], v[174:177], v[206:209], v[16:19]
	s_setprio 0
	s_barrier
; #define PG8_STAGE(bufoff, gbase, voff) do { _Pragma("unroll") for (int _i = 0; _i < 2; ++_i) \
;         __builtin_amdgcn_global_load_lds((const unsigned*)((const char*)(gbase) + (voff)[_i]), (LAS unsigned*)(lds + (bufoff) + ldsw + _i * 8192), 16, 0, 0); } while (0)
; #define PG8_LDA(dst, b, h) do { _Pragma("unroll") for (int m = 0; m < 4; ++m) _Pragma("unroll") for (int k = 0; k < 2; ++k) dst[m][k] = *(const LAS h16x8*)(lds + PG8_SA(b, h) + aoff + m * 2048 + k * 1024); } while (0)
; #define PG8_LDB(dst, b, h) do { _Pragma("unroll") for (int n = 0; n < 2; ++n) _Pragma("unroll") for (int k = 0; k < 2; ++k) dst[n][k] = *(const LAS h16x8*)(lds + PG8_SB(b, h) + boff + n * 2048 + k * 1024); } while (0)
; #define PG8_MMA(ai, bj, At, Bt) do { __builtin_amdgcn_s_setprio(1); _Pragma("unroll") for (int m = 0; m < 4; ++m) _Pragma("unroll") for (int n = 0; n < 2; ++n) _Pragma("unroll") for (int k = 0; k < 2; ++k) \
;         acc[ai][bj][m][n] = __builtin_amdgcn_mfma_f32_16x16x32_f16(Bt[n][k], At[m][k], acc[ai][bj][m][n], 0, 0, 0); __builtin_amdgcn_s_setprio(0); } while (0)
; #define PG8_WAIT_V(n) asm volatile("s_waitcnt vmcnt(" #n ")" ::: "memory")
; #define PG8_WAIT_L(n) asm volatile("s_waitcnt lgkmcnt(" #n ")" ::: "memory")
; #define PG8_BAR __builtin_amdgcn_s_barrier()
; #define PG8_SCHED __builtin_amdgcn_sched_barrier(0)
; template <class Epi>
; __device__ __forceinline__ void gemm_phase(LAS unsigned char* lds, const Gemm g, const StaticOrder& S, const Epi& E) {
;     ...
;             PG8_STAGE(PG8_SB(0, 1), b2 + hstep, voffB);
;             PG8_WAIT_V(6); PG8_BAR; PG8_MMA(1, 1, At, B1); PG8_BAR;
;             PG8_LDB(B0, 1, 0); PG8_SCHED; PG8_LDA(At, 1, 0); PG8_STAGE(PG8_SA(0, 1), a2 + hstep, voffA);
;             PG8_WAIT_L(8); PG8_BAR; PG8_WAIT_L(0); PG8_MMA(0, 0, At, B0); PG8_BAR; PG8_SCHED;
;             PG8_LDB(B1, 1, 1); PG8_STAGE(PG8_SB(1, 0), b3, voffB);
;             PG8_BAR; PG8_WAIT_L(0); PG8_MMA(0, 1, At, B1); PG8_BAR;
;             PG8_LDA(At, 1, 1); PG8_STAGE(PG8_SA(1, 0), a3, voffA);
	s_add_u32 vcc_lo, s38, 0x40000
	s_addc_u32 vcc_hi, s39, 0
	s_add_i32 s80, s61, s45
	v_lshl_add_u64 v[162:163], vcc, 0, v[128:129]
	s_mov_b32 m0, s80
	s_nop 0
	global_load_lds_dwordx4 v[162:163], off
	v_lshl_add_u64 v[162:163], vcc, 0, v[138:139]
	s_add_i32 m0, s80, 0x2000
	s_nop 0
	global_load_lds_dwordx4 v[162:163], off
	s_waitcnt vmcnt(6)
	s_barrier
	s_setprio 1
	v_mfma_f32_16x16x32_f16 v[44:47], v[210:213], v[178:181], v[44:47]
	v_mfma_f32_16x16x32_f16 v[40:43], v[218:221], v[178:181], v[40:43]
	v_mfma_f32_16x16x32_f16 v[28:31], v[210:213], v[186:189], v[28:31]
	v_mfma_f32_16x16x32_f16 v[24:27], v[218:221], v[186:189], v[24:27]
	v_mfma_f32_16x16x32_f16 v[12:15], v[210:213], v[194:197], v[12:15]
	v_mfma_f32_16x16x32_f16 v[8:11], v[218:221], v[194:197], v[8:11]
	v_mfma_f32_16x16x32_f16 v[4:7], v[210:213], v[202:205], v[4:7]
	v_mfma_f32_16x16x32_f16 v[0:3], v[218:221], v[202:205], v[0:3]
	v_mfma_f32_16x16x32_f16 v[44:47], v[214:217], v[182:185], v[44:47]
	v_mfma_f32_16x16x32_f16 v[40:43], v[228:231], v[182:185], v[40:43]
	v_mfma_f32_16x16x32_f16 v[28:31], v[214:217], v[190:193], v[28:31]
	v_mfma_f32_16x16x32_f16 v[24:27], v[228:231], v[190:193], v[24:27]
	v_mfma_f32_16x16x32_f16 v[12:15], v[214:217], v[198:201], v[12:15]
	v_mfma_f32_16x16x32_f16 v[8:11], v[228:231], v[198:201], v[8:11]
	v_mfma_f32_16x16x32_f16 v[4:7], v[214:217], v[206:209], v[4:7]
	v_mfma_f32_16x16x32_f16 v[0:3], v[228:231], v[206:209], v[0:3]
	s_setprio 0
	s_add_i32 s80, 0, 0x18000
	v_add_u32_e32 v161, s80, v137
	s_barrier
	ds_read_b128 v[162:165], v161
	ds_read_b128 v[166:169], v161 offset:1024
	ds_read_b128 v[170:173], v161 offset:2048
	ds_read_b128 v[174:177], v161 offset:3072
	s_add_u32 s42, s42, 0x40000
	s_addc_u32 s43, s43, 0
	s_mov_b32 m0, s54
	v_lshl_add_u64 v[210:211], s[42:43], 0, v[144:145]
	ds_read_b128 v[178:181], v159 offset:32768
	ds_read_b128 v[182:185], v159 offset:33792
	ds_read_b128 v[186:189], v159 offset:34816
	ds_read_b128 v[190:193], v159 offset:35840
	ds_read_b128 v[194:197], v159 offset:36864
	ds_read_b128 v[198:201], v159 offset:37888
	ds_read_b128 v[202:205], v159 offset:38912
	ds_read_b128 v[206:209], v159 offset:39936
	global_load_lds_dwordx4 v[210:211], off
	v_lshl_add_u64 v[210:211], s[42:43], 0, v[140:141]
	s_mov_b32 m0, s55
	s_nop 0
	global_load_lds_dwordx4 v[210:211], off
	s_waitcnt lgkmcnt(8)
	s_barrier
	s_waitcnt lgkmcnt(0)
	s_setprio 1
	s_waitcnt lgkmcnt(0)
	v_mfma_f32_16x16x32_f16 v[124:127], v[162:165], v[178:181], v[124:127]
	v_mfma_f32_16x16x32_f16 v[120:123], v[170:173], v[178:181], v[120:123]
	v_mfma_f32_16x16x32_f16 v[116:119], v[162:165], v[186:189], v[116:119]
	v_mfma_f32_16x16x32_f16 v[112:115], v[170:173], v[186:189], v[112:115]
	v_mfma_f32_16x16x32_f16 v[100:103], v[162:165], v[194:197], v[100:103]
	v_mfma_f32_16x16x32_f16 v[96:99], v[170:173], v[194:197], v[96:99]
	v_mfma_f32_16x16x32_f16 v[84:87], v[162:165], v[202:205], v[84:87]
	v_mfma_f32_16x16x32_f16 v[80:83], v[170:173], v[202:205], v[80:83]
	v_mfma_f32_16x16x32_f16 v[124:127], v[166:169], v[182:185], v[124:127]
	v_mfma_f32_16x16x32_f16 v[120:123], v[174:177], v[182:185], v[120:123]
	v_mfma_f32_16x16x32_f16 v[116:119], v[166:169], v[190:193], v[116:119]
	v_mfma_f32_16x16x32_f16 v[112:115], v[174:177], v[190:193], v[112:115]
	v_mfma_f32_16x16x32_f16 v[100:103], v[166:169], v[198:201], v[100:103]
	v_mfma_f32_16x16x32_f16 v[96:99], v[174:177], v[198:201], v[96:99]
	v_mfma_f32_16x16x32_f16 v[84:87], v[166:169], v[206:209], v[84:87]
	v_mfma_f32_16x16x32_f16 v[80:83], v[174:177], v[206:209], v[80:83]
	s_setprio 0
	s_barrier
	s_add_i32 s42, 0, 0x1c000
	s_add_i32 s43, s80, s45
	v_add_u32_e32 v161, s42, v137
	v_lshl_add_u64 v[222:223], v[222:223], 0, s[0:1]
	s_mov_b32 m0, s43
	ds_read_b128 v[210:213], v161
	ds_read_b128 v[214:217], v161 offset:1024
	ds_read_b128 v[218:221], v161 offset:2048
	ds_read_b128 v[228:231], v161 offset:3072
	global_load_lds_dwordx4 v[222:223], off
	v_lshl_add_u64 v[222:223], v[232:233], 0, s[0:1]
	s_add_i32 m0, s43, 0x2000
	s_nop 0
	global_load_lds_dwordx4 v[222:223], off
	s_barrier
	s_waitcnt lgkmcnt(0)
	s_setprio 1
	s_waitcnt lgkmcnt(0)
	v_mfma_f32_16x16x32_f16 v[108:111], v[210:213], v[178:181], v[108:111]
	v_mfma_f32_16x16x32_f16 v[104:107], v[218:221], v[178:181], v[104:107]
	v_mfma_f32_16x16x32_f16 v[92:95], v[210:213], v[186:189], v[92:95]
	v_mfma_f32_16x16x32_f16 v[88:91], v[218:221], v[186:189], v[88:91]
	v_mfma_f32_16x16x32_f16 v[76:79], v[210:213], v[194:197], v[76:79]
	v_mfma_f32_16x16x32_f16 v[72:75], v[218:221], v[194:197], v[72:75]
	v_mfma_f32_16x16x32_f16 v[68:71], v[210:213], v[202:205], v[68:71]
	v_mfma_f32_16x16x32_f16 v[64:67], v[218:221], v[202:205], v[64:67]
	v_mfma_f32_16x16x32_f16 v[108:111], v[214:217], v[182:185], v[108:111]
	v_mfma_f32_16x16x32_f16 v[104:107], v[228:231], v[182:185], v[104:107]
	v_mfma_f32_16x16x32_f16 v[92:95], v[214:217], v[190:193], v[92:95]
	v_mfma_f32_16x16x32_f16 v[88:91], v[228:231], v[190:193], v[88:91]
	v_mfma_f32_16x16x32_f16 v[76:79], v[214:217], v[198:201], v[76:79]
	v_mfma_f32_16x16x32_f16 v[72:75], v[228:231], v[198:201], v[72:75]
	v_mfma_f32_16x16x32_f16 v[68:71], v[214:217], v[206:209], v[68:71]
	v_mfma_f32_16x16x32_f16 v[64:67], v[228:231], v[206:209], v[64:67]
	s_setprio 0
	s_mov_b32 m0, s56
	v_lshl_add_u64 v[222:223], v[234:235], 0, s[0:1]
	s_barrier
	ds_read_b128 v[178:181], v159 offset:49152
	ds_read_b128 v[182:185], v159 offset:50176
	ds_read_b128 v[186:189], v159 offset:51200
	ds_read_b128 v[190:193], v159 offset:52224
	ds_read_b128 v[194:197], v159 offset:53248
	ds_read_b128 v[198:201], v159 offset:54272
	ds_read_b128 v[202:205], v159 offset:55296
	ds_read_b128 v[206:209], v159 offset:56320
	global_load_lds_dwordx4 v[222:223], off
	v_lshl_add_u64 v[222:223], v[236:237], 0, s[0:1]
	s_mov_b32 m0, s57
	s_nop 0
	global_load_lds_dwordx4 v[222:223], off
	s_barrier
; #define PG8_WAIT_V(n) asm volatile("s_waitcnt vmcnt(" #n ")" ::: "memory")
; #define PG8_WAIT_L(n) asm volatile("s_waitcnt lgkmcnt(" #n ")" ::: "memory")
; #define PG8_BAR __builtin_amdgcn_s_barrier()
; template <class Epi>
; __device__ __forceinline__ void gemm_phase(LAS unsigned char* lds, const Gemm g, const StaticOrder& S, const Epi& E) {
;     ...
;             PG8_BAR; PG8_WAIT_L(0); PG8_MMA(1, 0, At, B0); PG8_BAR; PG8_SCHED;
;             PG8_STAGE(PG8_SB(1, 1), b3 + hstep, voffB);
;             PG8_WAIT_V(6); PG8_BAR; PG8_MMA(1, 1, At, B1); PG8_BAR;
;         }
;     __device__ __forceinline__ void operator()(const f32x4 (&acc)[2][2][4][2], const pg8::Unit& u, int wr, int wc, int fr, int fq) const {
;         const int row0 = u.pm * 256 + wr * 64 + fr, col0 = u.pn * 256 + wc * 32 + 8 * fq;
; #pragma unroll
;         for (int ai = 0; ai < 2; ++ai)
; #pragma unroll
;             for (int m = 0; m < 4; ++m) {
;                 const int row = row0 + ai * 128 + m * 16;
;                 float ss = 0.f, rstd = 1.f;
;                 if (MODE == 2) rstd = rsqrtf(rowss[row] * (1.f / 1024.f) + EPS);
; #pragma unroll
;                 for (int bj = 0; bj < 2; ++bj) {
;                     const int c = col0 + bj * 128;
;                     f32x4 v0 = acc[ai][bj][m][0], v1 = acc[ai][bj][m][1];
;                     if (MODE == 1) {
;                         const float* rp = res + (size_t)row * ldres + c;
;                         v0 += *(const f32x4*)rp; v1 += *(const f32x4*)(rp + 4);
;                     }
;                     if (MODE == 3) {
;                         const h16x8 r8 = *(const h16x8*)(res16 + (size_t)row * ldres + c);
; #pragma unroll
;                         for (int j = 0; j < 4; ++j) { v0[j] += (float)r8[j]; v1[j] += (float)r8[4 + j]; }
;                     }
;                     if (MODE == 1 || MODE == 3) {
;                         ss += v0[0] * v0[0] + v0[1] * v0[1] + v0[2] * v0[2] + v0[3] * v0[3] + v1[0] * v1[0] + v1[1] * v1[1] + v1[2] * v1[2] + v1[3] * v1[3];
;                     }
;                     if (MODE == 2) {
; #pragma unroll
;                         for (int j = 0; j < 4; ++j) { float a = fmaxf(v0[j] * rstd, 0.f), b = fmaxf(v1[j] * rstd, 0.f); v0[j] = a * a; v1[j] = b * b; }
;                     }
;                     *(h16x8*)(o16 + (size_t)row * ld16 + c) = pack8(v0, v1);
	s_waitcnt lgkmcnt(0)
	s_setprio 1
	s_waitcnt lgkmcnt(0)
	v_mfma_f32_16x16x32_f16 v[60:63], v[162:165], v[178:181], v[60:63]
	v_mfma_f32_16x16x32_f16 v[56:59], v[170:173], v[178:181], v[56:59]
	v_mfma_f32_16x16x32_f16 v[52:55], v[162:165], v[186:189], v[52:55]
	v_mfma_f32_16x16x32_f16 v[48:51], v[170:173], v[186:189], v[48:51]
	v_mfma_f32_16x16x32_f16 v[36:39], v[162:165], v[194:197], v[36:39]
	v_mfma_f32_16x16x32_f16 v[32:35], v[170:173], v[194:197], v[32:35]
	v_mfma_f32_16x16x32_f16 v[20:23], v[162:165], v[202:205], v[20:23]
	v_mfma_f32_16x16x32_f16 v[16:19], v[170:173], v[202:205], v[16:19]
	v_mfma_f32_16x16x32_f16 v[60:63], v[166:169], v[182:185], v[60:63]
	v_mfma_f32_16x16x32_f16 v[56:59], v[174:177], v[182:185], v[56:59]
	v_mfma_f32_16x16x32_f16 v[52:55], v[166:169], v[190:193], v[52:55]
	v_mfma_f32_16x16x32_f16 v[48:51], v[174:177], v[190:193], v[48:51]
	v_mfma_f32_16x16x32_f16 v[36:39], v[166:169], v[198:201], v[36:39]
	v_mfma_f32_16x16x32_f16 v[32:35], v[174:177], v[198:201], v[32:35]
	v_mfma_f32_16x16x32_f16 v[20:23], v[166:169], v[206:209], v[20:23]
	v_mfma_f32_16x16x32_f16 v[16:19], v[174:177], v[206:209], v[16:19]
	s_setprio 0
	s_barrier
	s_add_u32 s38, s38, 0x40080
	s_addc_u32 s39, s39, 0
	s_add_i32 s42, s42, s45
	v_lshl_add_u64 v[162:163], s[38:39], 0, v[128:129]
	s_mov_b32 m0, s42
	s_nop 0
	global_load_lds_dwordx4 v[162:163], off
	v_lshl_add_u64 v[162:163], s[38:39], 0, v[138:139]
	s_add_i32 m0, s42, 0x2000
	s_nop 0
	global_load_lds_dwordx4 v[162:163], off
	s_waitcnt vmcnt(6)
	s_barrier
	s_setprio 1
	v_mfma_f32_16x16x32_f16 v[44:47], v[210:213], v[178:181], v[44:47]
	v_mfma_f32_16x16x32_f16 v[40:43], v[218:221], v[178:181], v[40:43]
	v_mfma_f32_16x16x32_f16 v[28:31], v[210:213], v[186:189], v[28:31]
	v_mfma_f32_16x16x32_f16 v[24:27], v[218:221], v[186:189], v[24:27]
	v_mfma_f32_16x16x32_f16 v[12:15], v[210:213], v[194:197], v[12:15]
	v_mfma_f32_16x16x32_f16 v[8:11], v[218:221], v[194:197], v[8:11]
	v_mfma_f32_16x16x32_f16 v[4:7], v[210:213], v[202:205], v[4:7]
	v_mfma_f32_16x16x32_f16 v[0:3], v[218:221], v[202:205], v[0:3]
	v_mfma_f32_16x16x32_f16 v[44:47], v[214:217], v[182:185], v[44:47]
	v_mfma_f32_16x16x32_f16 v[40:43], v[228:231], v[182:185], v[40:43]
	v_mfma_f32_16x16x32_f16 v[28:31], v[214:217], v[190:193], v[28:31]
	v_mfma_f32_16x16x32_f16 v[24:27], v[228:231], v[190:193], v[24:27]
	v_mfma_f32_16x16x32_f16 v[12:15], v[214:217], v[198:201], v[12:15]
	v_mfma_f32_16x16x32_f16 v[8:11], v[228:231], v[198:201], v[8:11]
	v_mfma_f32_16x16x32_f16 v[4:7], v[214:217], v[206:209], v[4:7]
	v_mfma_f32_16x16x32_f16 v[0:3], v[228:231], v[206:209], v[0:3]
	s_setprio 0
	s_add_i32 s96, s96, 2
	s_add_u32 s34, s34, 0x100
	s_addc_u32 s35, s35, 0
	s_add_u32 s94, s94, 0x100
	s_addc_u32 s95, s95, 0
	s_cmp_gt_u32 s96, 13
	s_barrier
	s_cbranch_scc0 .LBB0_84
	v_lshl_add_u32 v161, s10, 8, v135
	v_lshl_or_b32 v162, s63, 8, v143
	v_and_b32_e32 v164, 0x60, v143
	v_add_lshl_u32 v162, v162, v164, 1
	v_mov_b32_e32 v163, 0
	v_mov_b64_e32 v[166:167], s[90:91]
	v_mad_i64_i32 v[164:165], s[34:35], v161, s62, v[166:167]
	v_lshl_add_u64 v[164:165], v[164:165], 0, v[162:163]
	v_and_b32_e32 v168, 8, v135
	v_cmp_eq_u32_e64 s[98:99], 0, v168
	v_mov_b32_e32 v168, 0xffff1040
	v_cndmask_b32_e64 v170, v168, 0, s[98:99]
	v_cndmask_b32_e64 v171, -1, 0, s[98:99]
	v_mov_b32_e32 v168, 0xf040
	v_cndmask_b32_e64 v172, 0, v168, s[98:99]
	v_mov_b32_e32 v173, 0
	s_mov_b32 s100, 0x1e000
	s_mov_b32 s101, 0
	v_cvt_pk_f16_f32 v124, v124, v125
	v_cvt_pk_f16_f32 v125, v126, v127
	v_cvt_pk_f16_f32 v126, v120, v121
	v_cvt_pk_f16_f32 v127, v122, v123
	v_cvt_pk_f16_f32 v108, v108, v109
	v_cvt_pk_f16_f32 v109, v110, v111
	v_cvt_pk_f16_f32 v110, v104, v105
	v_cvt_pk_f16_f32 v111, v106, v107
	s_nop 1
	v_mov_b32_dpp v176, v108 row_ror:8 row_mask:0xf bank_mask:0xf
	v_mov_b32_dpp v177, v109 row_ror:8 row_mask:0xf bank_mask:0xf
	v_mov_b32_dpp v178, v110 row_ror:8 row_mask:0xf bank_mask:0xf
	v_mov_b32_dpp v179, v111 row_ror:8 row_mask:0xf bank_mask:0xf
	v_cndmask_b32_e64 v108, v176, v124, s[98:99]
	v_cndmask_b32_e64 v109, v177, v125, s[98:99]
	v_cndmask_b32_e64 v110, v178, v126, s[98:99]
	v_cndmask_b32_e64 v111, v179, v127, s[98:99]
	v_cndmask_b32_e64 v176, v124, v176, s[98:99]
	v_cndmask_b32_e64 v177, v125, v177, s[98:99]
	v_cndmask_b32_e64 v178, v126, v178, s[98:99]
	v_cndmask_b32_e64 v179, v127, v179, s[98:99]
	v_lshl_add_u64 v[180:181], v[164:165], 0, v[170:171]
	v_lshl_add_u64 v[182:183], v[164:165], 0, v[172:173]
	global_store_dwordx4 v[180:181], v[108:111], off sc0 sc1
	global_store_dwordx4 v[182:183], v[176:179], off sc0 sc1
	v_lshl_add_u64 v[164:165], v[164:165], 0, s[100:101]
	v_cvt_pk_f16_f32 v116, v116, v117
	v_cvt_pk_f16_f32 v117, v118, v119
	v_cvt_pk_f16_f32 v118, v112, v113
	v_cvt_pk_f16_f32 v119, v114, v115
	v_cvt_pk_f16_f32 v92, v92, v93
	v_cvt_pk_f16_f32 v93, v94, v95
	v_cvt_pk_f16_f32 v94, v88, v89
	v_cvt_pk_f16_f32 v95, v90, v91
	s_nop 1
	v_mov_b32_dpp v184, v92 row_ror:8 row_mask:0xf bank_mask:0xf
	v_mov_b32_dpp v185, v93 row_ror:8 row_mask:0xf bank_mask:0xf
	v_mov_b32_dpp v186, v94 row_ror:8 row_mask:0xf bank_mask:0xf
	v_mov_b32_dpp v187, v95 row_ror:8 row_mask:0xf bank_mask:0xf
	v_cndmask_b32_e64 v92, v184, v116, s[98:99]
	v_cndmask_b32_e64 v93, v185, v117, s[98:99]
	v_cndmask_b32_e64 v94, v186, v118, s[98:99]
	v_cndmask_b32_e64 v95, v187, v119, s[98:99]
	v_cndmask_b32_e64 v184, v116, v184, s[98:99]
	v_cndmask_b32_e64 v185, v117, v185, s[98:99]
	v_cndmask_b32_e64 v186, v118, v186, s[98:99]
	v_cndmask_b32_e64 v187, v119, v187, s[98:99]
	v_lshl_add_u64 v[188:189], v[164:165], 0, v[170:171]
	v_lshl_add_u64 v[190:191], v[164:165], 0, v[172:173]
;     __device__ __forceinline__ void operator()(const f32x4 (&acc)[2][2][4][2], const pg8::Unit& u, int wr, int wc, int fr, int fq) const {
;     ...
;         for (int ai = 0; ai < 2; ++ai)
; #pragma unroll
;             for (int m = 0; m < 4; ++m) {
;                 const int row = row0 + ai * 128 + m * 16;
;                 float ss = 0.f, rstd = 1.f;
;                 if (MODE == 2) rstd = rsqrtf(rowss[row] * (1.f / 1024.f) + EPS);
; #pragma unroll
;                 for (int bj = 0; bj < 2; ++bj) {
;                     const int c = col0 + bj * 128;
;                     f32x4 v0 = acc[ai][bj][m][0], v1 = acc[ai][bj][m][1];
;                     if (MODE == 1) {
;                         const float* rp = res + (size_t)row * ldres + c;
;                         v0 += *(const f32x4*)rp; v1 += *(const f32x4*)(rp + 4);
;                     }
;                     if (MODE == 3) {
;                         const h16x8 r8 = *(const h16x8*)(res16 + (size_t)row * ldres + c);
; #pragma unroll
;                         for (int j = 0; j < 4; ++j) { v0[j] += (float)r8[j]; v1[j] += (float)r8[4 + j]; }
;                     }
;                     if (MODE == 1 || MODE == 3) {
;                         ss += v0[0] * v0[0] + v0[1] * v0[1] + v0[2] * v0[2] + v0[3] * v0[3] + v1[0] * v1[0] + v1[1] * v1[1] + v1[2] * v1[2] + v1[3] * v1[3];
;                     }
;                     if (MODE == 2) {
; #pragma unroll
;                         for (int j = 0; j < 4; ++j) { float a = fmaxf(v0[j] * rstd, 0.f), b = fmaxf(v1[j] * rstd, 0.f); v0[j] = a * a; v1[j] = b * b; }
;                     }
;                     *(h16x8*)(o16 + (size_t)row * ld16 + c) = pack8(v0, v1);
	global_store_dwordx4 v[188:189], v[92:95], off sc0 sc1
	global_store_dwordx4 v[190:191], v[184:187], off sc0 sc1
	v_lshl_add_u64 v[164:165], v[164:165], 0, s[100:101]
	v_cvt_pk_f16_f32 v100, v100, v101
	v_cvt_pk_f16_f32 v101, v102, v103
	v_cvt_pk_f16_f32 v102, v96, v97
	v_cvt_pk_f16_f32 v103, v98, v99
	v_cvt_pk_f16_f32 v76, v76, v77
	v_cvt_pk_f16_f32 v77, v78, v79
	v_cvt_pk_f16_f32 v78, v72, v73
	v_cvt_pk_f16_f32 v79, v74, v75
	s_nop 1
	v_mov_b32_dpp v176, v76 row_ror:8 row_mask:0xf bank_mask:0xf
	v_mov_b32_dpp v177, v77 row_ror:8 row_mask:0xf bank_mask:0xf
	v_mov_b32_dpp v178, v78 row_ror:8 row_mask:0xf bank_mask:0xf
	v_mov_b32_dpp v179, v79 row_ror:8 row_mask:0xf bank_mask:0xf
	v_cndmask_b32_e64 v76, v176, v100, s[98:99]
	v_cndmask_b32_e64 v77, v177, v101, s[98:99]
	v_cndmask_b32_e64 v78, v178, v102, s[98:99]
	v_cndmask_b32_e64 v79, v179, v103, s[98:99]
	v_cndmask_b32_e64 v176, v100, v176, s[98:99]
	v_cndmask_b32_e64 v177, v101, v177, s[98:99]
	v_cndmask_b32_e64 v178, v102, v178, s[98:99]
	v_cndmask_b32_e64 v179, v103, v179, s[98:99]
	v_lshl_add_u64 v[180:181], v[164:165], 0, v[170:171]
	v_lshl_add_u64 v[182:183], v[164:165], 0, v[172:173]
	global_store_dwordx4 v[180:181], v[76:79], off sc0 sc1
	global_store_dwordx4 v[182:183], v[176:179], off sc0 sc1
	v_lshl_add_u64 v[164:165], v[164:165], 0, s[100:101]
	v_cvt_pk_f16_f32 v84, v84, v85
	v_cvt_pk_f16_f32 v85, v86, v87
	v_cvt_pk_f16_f32 v86, v80, v81
	v_cvt_pk_f16_f32 v87, v82, v83
	v_cvt_pk_f16_f32 v68, v68, v69
	v_cvt_pk_f16_f32 v69, v70, v71
	v_cvt_pk_f16_f32 v70, v64, v65
	v_cvt_pk_f16_f32 v71, v66, v67
	s_nop 1
	v_mov_b32_dpp v184, v68 row_ror:8 row_mask:0xf bank_mask:0xf
	v_mov_b32_dpp v185, v69 row_ror:8 row_mask:0xf bank_mask:0xf
	v_mov_b32_dpp v186, v70 row_ror:8 row_mask:0xf bank_mask:0xf
	v_mov_b32_dpp v187, v71 row_ror:8 row_mask:0xf bank_mask:0xf
	v_cndmask_b32_e64 v68, v184, v84, s[98:99]
	v_cndmask_b32_e64 v69, v185, v85, s[98:99]
	v_cndmask_b32_e64 v70, v186, v86, s[98:99]
	v_cndmask_b32_e64 v71, v187, v87, s[98:99]
	v_cndmask_b32_e64 v184, v84, v184, s[98:99]
	v_cndmask_b32_e64 v185, v85, v185, s[98:99]
	v_cndmask_b32_e64 v186, v86, v186, s[98:99]
	v_cndmask_b32_e64 v187, v87, v187, s[98:99]
	v_lshl_add_u64 v[188:189], v[164:165], 0, v[170:171]
	v_lshl_add_u64 v[190:191], v[164:165], 0, v[172:173]
	global_store_dwordx4 v[188:189], v[68:71], off sc0 sc1
	global_store_dwordx4 v[190:191], v[184:187], off sc0 sc1
	v_add_co_u32_e32 v164, vcc, 0x96000, v164
	s_nop 1
	v_addc_co_u32_e32 v165, vcc, 0, v165, vcc
	v_cvt_pk_f16_f32 v60, v60, v61
	v_cvt_pk_f16_f32 v61, v62, v63
	v_cvt_pk_f16_f32 v62, v56, v57
	v_cvt_pk_f16_f32 v63, v58, v59
	v_cvt_pk_f16_f32 v44, v44, v45
	v_cvt_pk_f16_f32 v45, v46, v47
	v_cvt_pk_f16_f32 v46, v40, v41
	v_cvt_pk_f16_f32 v47, v42, v43
	s_nop 1
	v_mov_b32_dpp v176, v44 row_ror:8 row_mask:0xf bank_mask:0xf
	v_mov_b32_dpp v177, v45 row_ror:8 row_mask:0xf bank_mask:0xf
	v_mov_b32_dpp v178, v46 row_ror:8 row_mask:0xf bank_mask:0xf
	v_mov_b32_dpp v179, v47 row_ror:8 row_mask:0xf bank_mask:0xf
	v_cndmask_b32_e64 v44, v176, v60, s[98:99]
	v_cndmask_b32_e64 v45, v177, v61, s[98:99]
	v_cndmask_b32_e64 v46, v178, v62, s[98:99]
	v_cndmask_b32_e64 v47, v179, v63, s[98:99]
	v_cndmask_b32_e64 v176, v60, v176, s[98:99]
	v_cndmask_b32_e64 v177, v61, v177, s[98:99]
	v_cndmask_b32_e64 v178, v62, v178, s[98:99]
	v_cndmask_b32_e64 v179, v63, v179, s[98:99]
	v_lshl_add_u64 v[180:181], v[164:165], 0, v[170:171]
	v_lshl_add_u64 v[182:183], v[164:165], 0, v[172:173]
	global_store_dwordx4 v[180:181], v[44:47], off sc0 sc1
	global_store_dwordx4 v[182:183], v[176:179], off sc0 sc1
; #define PG8_WAIT_V(n) asm volatile("s_waitcnt vmcnt(" #n ")" ::: "memory")
; #define PG8_BAR __builtin_amdgcn_s_barrier()
; template <class Epi>
; __device__ __forceinline__ void gemm_phase(LAS unsigned char* lds, const Gemm g, const StaticOrder& S, const Epi& E) {
;     ...
;         if (!has_next) break;
; #pragma unroll
;         for (int a = 0; a < 2; ++a)
; #pragma unroll
;             for (int b = 0; b < 2; ++b)
; #pragma unroll
;                 for (int m = 0; m < 4; ++m)
; #pragma unroll
;                     for (int n = 0; n < 2; ++n) acc[a][b][m][n] = (f32x4){0.f, 0.f, 0.f, 0.f};
;         cur = nxt; cA = nA; cB = nB; ++ui;
;     }
;     PG8_WAIT_V(0);
;     if (wr == 0) PG8_BAR;
;     PG8_BAR;
;     __device__ __forceinline__ void operator()(const f32x4 (&acc)[2][2][4][2], const pg8::Unit& u, int wr, int wc, int fr, int fq) const {
;     ...
;         for (int ai = 0; ai < 2; ++ai)
; #pragma unroll
;             for (int m = 0; m < 4; ++m) {
;                 const int row = row0 + ai * 128 + m * 16;
;                 float ss = 0.f, rstd = 1.f;
;                 if (MODE == 2) rstd = rsqrtf(rowss[row] * (1.f / 1024.f) + EPS);
; #pragma unroll
;                 for (int bj = 0; bj < 2; ++bj) {
;                     const int c = col0 + bj * 128;
;                     f32x4 v0 = acc[ai][bj][m][0], v1 = acc[ai][bj][m][1];
;                     if (MODE == 1) {
;                         const float* rp = res + (size_t)row * ldres + c;
;                         v0 += *(const f32x4*)rp; v1 += *(const f32x4*)(rp + 4);
;                     }
;                     if (MODE == 3) {
;                         const h16x8 r8 = *(const h16x8*)(res16 + (size_t)row * ldres + c);
; #pragma unroll
;                         for (int j = 0; j < 4; ++j) { v0[j] += (float)r8[j]; v1[j] += (float)r8[4 + j]; }
;                     }
;                     if (MODE == 1 || MODE == 3) {
;                         ss += v0[0] * v0[0] + v0[1] * v0[1] + v0[2] * v0[2] + v0[3] * v0[3] + v1[0] * v1[0] + v1[1] * v1[1] + v1[2] * v1[2] + v1[3] * v1[3];
;                     }
;                     if (MODE == 2) {
; #pragma unroll
;                         for (int j = 0; j < 4; ++j) { float a = fmaxf(v0[j] * rstd, 0.f), b = fmaxf(v1[j] * rstd, 0.f); v0[j] = a * a; v1[j] = b * b; }
;                     }
;                     *(h16x8*)(o16 + (size_t)row * ld16 + c) = pack8(v0, v1);
	v_lshl_add_u64 v[164:165], v[164:165], 0, s[100:101]
	v_cvt_pk_f16_f32 v52, v52, v53
	v_cvt_pk_f16_f32 v53, v54, v55
	v_cvt_pk_f16_f32 v54, v48, v49
	v_cvt_pk_f16_f32 v55, v50, v51
	v_cvt_pk_f16_f32 v28, v28, v29
	v_cvt_pk_f16_f32 v29, v30, v31
	v_cvt_pk_f16_f32 v30, v24, v25
	v_cvt_pk_f16_f32 v31, v26, v27
	s_nop 1
	v_mov_b32_dpp v184, v28 row_ror:8 row_mask:0xf bank_mask:0xf
	v_mov_b32_dpp v185, v29 row_ror:8 row_mask:0xf bank_mask:0xf
	v_mov_b32_dpp v186, v30 row_ror:8 row_mask:0xf bank_mask:0xf
	v_mov_b32_dpp v187, v31 row_ror:8 row_mask:0xf bank_mask:0xf
	v_cndmask_b32_e64 v28, v184, v52, s[98:99]
	v_cndmask_b32_e64 v29, v185, v53, s[98:99]
	v_cndmask_b32_e64 v30, v186, v54, s[98:99]
	v_cndmask_b32_e64 v31, v187, v55, s[98:99]
	v_cndmask_b32_e64 v184, v52, v184, s[98:99]
	v_cndmask_b32_e64 v185, v53, v185, s[98:99]
	v_cndmask_b32_e64 v186, v54, v186, s[98:99]
	v_cndmask_b32_e64 v187, v55, v187, s[98:99]
	v_lshl_add_u64 v[188:189], v[164:165], 0, v[170:171]
	v_lshl_add_u64 v[190:191], v[164:165], 0, v[172:173]
	global_store_dwordx4 v[188:189], v[28:31], off sc0 sc1
	global_store_dwordx4 v[190:191], v[184:187], off sc0 sc1
	v_lshl_add_u64 v[164:165], v[164:165], 0, s[100:101]
	v_cvt_pk_f16_f32 v36, v36, v37
	v_cvt_pk_f16_f32 v37, v38, v39
	v_cvt_pk_f16_f32 v38, v32, v33
	v_cvt_pk_f16_f32 v39, v34, v35
	v_cvt_pk_f16_f32 v12, v12, v13
	v_cvt_pk_f16_f32 v13, v14, v15
	v_cvt_pk_f16_f32 v14, v8, v9
	v_cvt_pk_f16_f32 v15, v10, v11
	s_nop 1
	v_mov_b32_dpp v176, v12 row_ror:8 row_mask:0xf bank_mask:0xf
	v_mov_b32_dpp v177, v13 row_ror:8 row_mask:0xf bank_mask:0xf
	v_mov_b32_dpp v178, v14 row_ror:8 row_mask:0xf bank_mask:0xf
	v_mov_b32_dpp v179, v15 row_ror:8 row_mask:0xf bank_mask:0xf
	v_cndmask_b32_e64 v12, v176, v36, s[98:99]
	v_cndmask_b32_e64 v13, v177, v37, s[98:99]
	v_cndmask_b32_e64 v14, v178, v38, s[98:99]
	v_cndmask_b32_e64 v15, v179, v39, s[98:99]
	v_cndmask_b32_e64 v176, v36, v176, s[98:99]
	v_cndmask_b32_e64 v177, v37, v177, s[98:99]
	v_cndmask_b32_e64 v178, v38, v178, s[98:99]
	v_cndmask_b32_e64 v179, v39, v179, s[98:99]
	v_lshl_add_u64 v[180:181], v[164:165], 0, v[170:171]
	v_lshl_add_u64 v[182:183], v[164:165], 0, v[172:173]
	global_store_dwordx4 v[180:181], v[12:15], off sc0 sc1
	global_store_dwordx4 v[182:183], v[176:179], off sc0 sc1
	v_lshl_add_u64 v[164:165], v[164:165], 0, s[100:101]
	v_cvt_pk_f16_f32 v20, v20, v21
	v_cvt_pk_f16_f32 v21, v22, v23
	v_cvt_pk_f16_f32 v22, v16, v17
	v_cvt_pk_f16_f32 v23, v18, v19
	v_cvt_pk_f16_f32 v4, v4, v5
	v_cvt_pk_f16_f32 v5, v6, v7
	v_cvt_pk_f16_f32 v6, v0, v1
	v_cvt_pk_f16_f32 v7, v2, v3
	s_nop 1
	v_mov_b32_dpp v184, v4 row_ror:8 row_mask:0xf bank_mask:0xf
	v_mov_b32_dpp v185, v5 row_ror:8 row_mask:0xf bank_mask:0xf
	v_mov_b32_dpp v186, v6 row_ror:8 row_mask:0xf bank_mask:0xf
	v_mov_b32_dpp v187, v7 row_ror:8 row_mask:0xf bank_mask:0xf
	v_cndmask_b32_e64 v4, v184, v20, s[98:99]
	v_cndmask_b32_e64 v5, v185, v21, s[98:99]
	v_cndmask_b32_e64 v6, v186, v22, s[98:99]
	v_cndmask_b32_e64 v7, v187, v23, s[98:99]
	v_cndmask_b32_e64 v184, v20, v184, s[98:99]
	v_cndmask_b32_e64 v185, v21, v185, s[98:99]
	v_cndmask_b32_e64 v186, v22, v186, s[98:99]
	v_cndmask_b32_e64 v187, v23, v187, s[98:99]
	v_lshl_add_u64 v[188:189], v[164:165], 0, v[170:171]
	v_lshl_add_u64 v[190:191], v[164:165], 0, v[172:173]
	global_store_dwordx4 v[188:189], v[4:7], off sc0 sc1
	global_store_dwordx4 v[190:191], v[184:187], off sc0 sc1
	s_and_b64 vcc, exec, s[8:9]
	s_mov_b32 s63, s24
	s_mov_b32 s10, s26
	s_mov_b64 s[38:39], s[30:31]
	s_mov_b64 s[34:35], s[28:29]
	s_cbranch_vccz .LBB0_81
	s_waitcnt vmcnt(0)
	s_cmpk_gt_u32 s44, 0xff
	s_cbranch_scc1 .LBB0_88
	s_barrier
